# attention: running max only raised when the tile max exceeds it by more than 8 (log2 units), so the value waves skip most accumulator rescales
# speedup vs baseline: 1.0503x; 1.0149x over previous
.LBB0_409:
	s_cmp_ge_i32 s8, s27
	s_cbranch_scc1 .LBB0_413
	s_mul_hi_u32 s8, s8, 0xaaaaaaab
	s_lshr_b32 s8, s8, 1
	s_mul_i32 s8, s8, 0xfffe1400
	s_add_i32 s8, s28, s8
	v_add_u32_e32 v175, s8, v174
	ds_read_b128 v[176:179], v175
	ds_read_b128 v[180:183], v175 offset:32
	ds_read_b128 v[184:187], v175 offset:20992
	ds_read_b128 v[188:191], v175 offset:21024
	ds_read_b128 v[220:223], v175 offset:64
	ds_read_b128 v[224:227], v175 offset:21056
	ds_read_b128 v[228:231], v175 offset:96
	ds_read_b128 v[232:235], v175 offset:21088
	ds_read_b128 v[236:239], v175 offset:128
	ds_read_b128 v[240:243], v175 offset:21120
	s_mov_b32 s8, 0xf149f2ca
	s_waitcnt vmcnt(29) lgkmcnt(9)
	v_mfma_f32_32x32x16_bf16 v[18:33], v[176:179], v[34:37], 0
	ds_read_b128 v[176:179], v175 offset:160
	s_waitcnt vmcnt(28) lgkmcnt(9)
	v_mfma_f32_32x32x16_bf16 v[18:33], v[180:183], v[38:41], v[18:33]
	ds_read_b128 v[180:183], v175 offset:21152
	s_waitcnt lgkmcnt(9)
	v_mfma_f32_32x32x16_bf16 v[2:17], v[184:187], v[34:37], 0
	ds_read_b128 v[184:187], v175 offset:192
	s_waitcnt lgkmcnt(9)
	v_mfma_f32_32x32x16_bf16 v[2:17], v[188:191], v[38:41], v[2:17]
	ds_read_b128 v[188:191], v175 offset:21184
	s_waitcnt vmcnt(27) lgkmcnt(9)
	v_mfma_f32_32x32x16_bf16 v[18:33], v[220:223], v[42:45], v[18:33]
	ds_read_b128 v[220:223], v175 offset:224
	s_waitcnt lgkmcnt(9)
	v_mfma_f32_32x32x16_bf16 v[2:17], v[224:227], v[42:45], v[2:17]
	ds_read_b128 v[224:227], v175 offset:21216
	s_waitcnt vmcnt(26) lgkmcnt(9)
	v_mfma_f32_32x32x16_bf16 v[18:33], v[228:231], v[46:49], v[18:33]
	ds_read_b128 v[228:231], v175 offset:256
	s_waitcnt lgkmcnt(9)
	v_mfma_f32_32x32x16_bf16 v[2:17], v[232:235], v[46:49], v[2:17]
	ds_read_b128 v[232:235], v175 offset:21248
	s_waitcnt vmcnt(25) lgkmcnt(9)
	v_mfma_f32_32x32x16_bf16 v[18:33], v[236:239], v[50:53], v[18:33]
	ds_read_b128 v[236:239], v175 offset:288
	s_waitcnt lgkmcnt(9)
	v_mfma_f32_32x32x16_bf16 v[2:17], v[240:243], v[50:53], v[2:17]
	ds_read_b128 v[240:243], v175 offset:21280
	s_waitcnt vmcnt(24) lgkmcnt(9)
	v_mfma_f32_32x32x16_bf16 v[18:33], v[176:179], v[54:57], v[18:33]
	ds_read_b128 v[176:179], v175 offset:320
	s_waitcnt lgkmcnt(9)
	v_mfma_f32_32x32x16_bf16 v[2:17], v[180:183], v[54:57], v[2:17]
	ds_read_b128 v[180:183], v175 offset:21312
	s_waitcnt vmcnt(23) lgkmcnt(9)
	v_mfma_f32_32x32x16_bf16 v[18:33], v[184:187], v[58:61], v[18:33]
	ds_read_b128 v[184:187], v175 offset:352
	s_waitcnt lgkmcnt(9)
	v_mfma_f32_32x32x16_bf16 v[2:17], v[188:191], v[58:61], v[2:17]
	ds_read_b128 v[188:191], v175 offset:21344
	s_waitcnt vmcnt(22) lgkmcnt(9)
	v_mfma_f32_32x32x16_bf16 v[18:33], v[220:223], v[62:65], v[18:33]
	ds_read_b128 v[220:223], v175 offset:384
	s_waitcnt lgkmcnt(9)
	v_mfma_f32_32x32x16_bf16 v[2:17], v[224:227], v[62:65], v[2:17]
	ds_read_b128 v[224:227], v175 offset:21376
	s_waitcnt vmcnt(21) lgkmcnt(9)
	v_mfma_f32_32x32x16_bf16 v[18:33], v[228:231], v[66:69], v[18:33]
	ds_read_b128 v[228:231], v175 offset:416
	s_waitcnt lgkmcnt(9)
	v_mfma_f32_32x32x16_bf16 v[2:17], v[232:235], v[66:69], v[2:17]
	ds_read_b128 v[232:235], v175 offset:21408
	s_waitcnt vmcnt(20) lgkmcnt(9)
	v_mfma_f32_32x32x16_bf16 v[18:33], v[236:239], v[70:73], v[18:33]
	ds_read_b128 v[236:239], v175 offset:448
	s_waitcnt lgkmcnt(9)
	v_mfma_f32_32x32x16_bf16 v[2:17], v[240:243], v[70:73], v[2:17]
	ds_read_b128 v[240:243], v175 offset:21440
	s_waitcnt vmcnt(19) lgkmcnt(9)
	v_mfma_f32_32x32x16_bf16 v[18:33], v[176:179], v[74:77], v[18:33]
	ds_read_b128 v[176:179], v175 offset:480
	s_waitcnt lgkmcnt(9)
	v_mfma_f32_32x32x16_bf16 v[2:17], v[180:183], v[74:77], v[2:17]
	ds_read_b128 v[180:183], v175 offset:21472
	s_waitcnt vmcnt(18) lgkmcnt(9)
	v_mfma_f32_32x32x16_bf16 v[18:33], v[184:187], v[78:81], v[18:33]
	ds_read_b128 v[184:187], v175 offset:512
	s_waitcnt lgkmcnt(9)
	v_mfma_f32_32x32x16_bf16 v[2:17], v[188:191], v[78:81], v[2:17]
	ds_read_b128 v[188:191], v175 offset:21504
	s_waitcnt vmcnt(17) lgkmcnt(9)
	v_mfma_f32_32x32x16_bf16 v[18:33], v[220:223], v[82:85], v[18:33]
	ds_read_b128 v[220:223], v175 offset:544
	s_waitcnt lgkmcnt(9)
	v_mfma_f32_32x32x16_bf16 v[2:17], v[224:227], v[82:85], v[2:17]
	ds_read_b128 v[224:227], v175 offset:21536
	s_waitcnt vmcnt(16) lgkmcnt(9)
	v_mfma_f32_32x32x16_bf16 v[18:33], v[228:231], v[86:89], v[18:33]
	ds_read_b128 v[228:231], v175 offset:576
	s_waitcnt lgkmcnt(9)
	v_mfma_f32_32x32x16_bf16 v[2:17], v[232:235], v[86:89], v[2:17]
	ds_read_b128 v[232:235], v175 offset:608
	s_waitcnt vmcnt(15) lgkmcnt(9)
	v_mfma_f32_32x32x16_bf16 v[18:33], v[236:239], v[90:93], v[18:33]
	ds_read_b128 v[236:239], v175 offset:21568
	s_waitcnt lgkmcnt(9)
	v_mfma_f32_32x32x16_bf16 v[2:17], v[240:243], v[90:93], v[2:17]
	ds_read_b128 v[240:243], v175 offset:21600
	s_waitcnt vmcnt(14) lgkmcnt(9)
	v_mfma_f32_32x32x16_bf16 v[18:33], v[176:179], v[94:97], v[18:33]
	s_waitcnt lgkmcnt(8)
	v_mfma_f32_32x32x16_bf16 v[2:17], v[180:183], v[94:97], v[2:17]
	s_waitcnt vmcnt(13) lgkmcnt(7)
	v_mfma_f32_32x32x16_bf16 v[18:33], v[184:187], v[98:101], v[18:33]
	s_waitcnt lgkmcnt(6)
	v_mfma_f32_32x32x16_bf16 v[2:17], v[188:191], v[98:101], v[2:17]
	s_waitcnt vmcnt(12) lgkmcnt(5)
	v_mfma_f32_32x32x16_bf16 v[18:33], v[220:223], v[102:105], v[18:33]
	s_waitcnt lgkmcnt(4)
	v_mfma_f32_32x32x16_bf16 v[2:17], v[224:227], v[102:105], v[2:17]
	s_waitcnt vmcnt(11) lgkmcnt(3)
	v_mfma_f32_32x32x16_bf16 v[18:33], v[228:231], v[106:109], v[18:33]
	s_waitcnt vmcnt(10) lgkmcnt(2)
	v_mfma_f32_32x32x16_bf16 v[18:33], v[232:235], v[110:113], v[18:33]
	s_waitcnt lgkmcnt(1)
	v_mfma_f32_32x32x16_bf16 v[2:17], v[236:239], v[106:109], v[2:17]
	s_nop 9
	v_max3_f32 v175, v18, s8, v19
	v_max3_f32 v175, v175, v20, v21
	v_max3_f32 v175, v175, v22, v23
	v_max3_f32 v175, v175, v24, v25
	v_max3_f32 v175, v175, v26, v27
	v_max3_f32 v175, v175, v28, v29
	v_max3_f32 v175, v175, v30, v31
	s_waitcnt lgkmcnt(0)
	v_mfma_f32_32x32x16_bf16 v[2:17], v[240:243], v[110:113], v[2:17]
	v_max3_f32 v175, v175, v32, v33
	v_xor_b32_e32 v176, 32, v192
	v_add_u32_e32 v177, 64, v193
	v_cmp_lt_i32_e32 vcc, v176, v177
	s_and_b32 s8, s29, 4
	s_or_b32 s8, s8, s91
	v_cndmask_b32_e32 v176, v192, v176, vcc
	s_nop 4
	v_max3_f32 v175, v175, v2, v3
	v_max3_f32 v175, v175, v4, v5
	v_max3_f32 v175, v175, v6, v7
	v_max3_f32 v175, v175, v8, v9
	v_max3_f32 v175, v175, v10, v11
	v_max3_f32 v175, v175, v12, v13
	v_max3_f32 v175, v175, v14, v15
	v_max3_f32 v175, v175, v16, v17
	v_lshlrev_b32_e32 v176, 2, v176
	ds_bpermute_b32 v177, v176, v175
	s_mulk_i32 s8, 0x1080
	s_add_i32 s8, s8, 0
	s_add_i32 s8, s8, 0x1ec00
	s_waitcnt lgkmcnt(0)
	v_max3_f32 v175, v165, v175, v177
	v_sub_f32_e32 v177, v175, v165
	v_cmp_lt_f32_e32 vcc, 8.0, v177
	s_nop 1
	v_cndmask_b32_e32 v175, v165, v175, vcc
	v_sub_f32_e32 v18, v18, v175
	v_exp_f32_e32 v18, v18
	v_sub_f32_e32 v19, v19, v175
	v_exp_f32_e32 v19, v19
	v_sub_f32_e32 v20, v20, v175
	v_exp_f32_e32 v20, v20
	v_sub_f32_e32 v21, v21, v175
	v_exp_f32_e32 v21, v21
	v_sub_f32_e32 v22, v22, v175
	v_add_f32_e32 v177, 0, v18
	v_exp_f32_e32 v22, v22
	v_sub_f32_e32 v23, v23, v175
	v_add_f32_e32 v177, v177, v19
	v_exp_f32_e32 v23, v23
	v_sub_f32_e32 v24, v24, v175
	v_add_f32_e32 v177, v177, v20
	v_exp_f32_e32 v24, v24
	v_sub_f32_e32 v25, v25, v175
	v_add_f32_e32 v177, v177, v21
	v_exp_f32_e32 v25, v25
	v_sub_f32_e32 v26, v26, v175
	v_add_f32_e32 v177, v177, v22
	v_exp_f32_e32 v26, v26
	v_sub_f32_e32 v27, v27, v175
	v_add_f32_e32 v177, v177, v23
	v_exp_f32_e32 v27, v27
	v_sub_f32_e32 v28, v28, v175
	v_add_f32_e32 v177, v177, v24
	v_exp_f32_e32 v28, v28
	v_sub_f32_e32 v29, v29, v175
	v_add_f32_e32 v177, v177, v25
	v_exp_f32_e32 v29, v29
	v_sub_f32_e32 v30, v30, v175
	v_add_f32_e32 v177, v177, v26
	v_exp_f32_e32 v30, v30
	v_sub_f32_e32 v31, v31, v175
	v_add_f32_e32 v177, v177, v27
	v_exp_f32_e32 v31, v31
	v_sub_f32_e32 v32, v32, v175
	v_add_f32_e32 v177, v177, v28
	v_exp_f32_e32 v32, v32
	v_sub_f32_e32 v33, v33, v175
	v_add_f32_e32 v177, v177, v29
	v_exp_f32_e32 v33, v33
	v_sub_f32_e32 v2, v2, v175
	v_add_f32_e32 v177, v177, v30
	v_exp_f32_e32 v178, v2
	v_sub_f32_e32 v2, v3, v175
	v_add_f32_e32 v177, v177, v31
	v_exp_f32_e32 v179, v2
	v_sub_f32_e32 v2, v4, v175
	v_add_f32_e32 v177, v177, v32
	v_exp_f32_e32 v180, v2
	v_sub_f32_e32 v2, v5, v175
	v_add_f32_e32 v177, v177, v33
	v_exp_f32_e32 v5, v2
	v_sub_f32_e32 v3, v6, v175
	v_add_f32_e32 v2, v177, v178
	v_exp_f32_e32 v177, v3
	v_sub_f32_e32 v3, v7, v175
	v_add_f32_e32 v2, v2, v179
	v_exp_f32_e32 v181, v3
	v_sub_f32_e32 v3, v8, v175
	v_add_f32_e32 v2, v2, v180
	v_exp_f32_e32 v182, v3
	v_sub_f32_e32 v3, v9, v175
	v_add_f32_e32 v2, v2, v5
	v_exp_f32_e32 v183, v3
	v_sub_f32_e32 v3, v10, v175
	v_add_f32_e32 v2, v2, v177
	v_exp_f32_e32 v10, v3
	v_sub_f32_e32 v3, v11, v175
	v_add_f32_e32 v2, v2, v181
	v_exp_f32_e32 v11, v3
	v_sub_f32_e32 v3, v12, v175
	v_add_f32_e32 v2, v2, v182
	v_exp_f32_e32 v12, v3
	v_sub_f32_e32 v3, v13, v175
	v_add_f32_e32 v2, v2, v183
	v_exp_f32_e32 v13, v3
	v_sub_f32_e32 v3, v14, v175
	v_add_f32_e32 v2, v2, v10
	v_exp_f32_e32 v14, v3
	v_sub_f32_e32 v3, v15, v175
	v_add_f32_e32 v2, v2, v11
	v_exp_f32_e32 v15, v3
	v_sub_f32_e32 v3, v16, v175
	v_add_f32_e32 v2, v2, v12
	v_exp_f32_e32 v16, v3
	v_sub_f32_e32 v3, v17, v175
	v_add_f32_e32 v2, v2, v13
	v_exp_f32_e32 v17, v3
	v_add_f32_e32 v2, v2, v14
	v_add_f32_e32 v2, v2, v15
	v_add_f32_e32 v2, v2, v16
	v_add_f32_e32 v2, v2, v17
	v_sub_f32_e32 v165, v165, v175
	ds_bpermute_b32 v4, v176, v2
	v_exp_f32_e32 v3, v165
	v_add_u32_e32 v165, s8, v169
	v_cvt_pk_bf16_f32 v6, v18, v19
	v_cvt_pk_bf16_f32 v7, v20, v21
	v_cvt_pk_bf16_f32 v8, v22, v23
	v_cvt_pk_bf16_f32 v9, v24, v25
	ds_write_b128 v165, v[6:9]
	v_cvt_pk_bf16_f32 v6, v26, v27
	v_cvt_pk_bf16_f32 v7, v28, v29
	v_cvt_pk_bf16_f32 v8, v30, v31
	v_cvt_pk_bf16_f32 v9, v32, v33
	ds_write_b128 v165, v[6:9] offset:1024
	v_cvt_pk_bf16_f32 v6, v178, v179
	v_cvt_pk_bf16_f32 v7, v180, v5
	v_cvt_pk_bf16_f32 v8, v177, v181
	v_cvt_pk_bf16_f32 v9, v182, v183
	ds_write_b128 v165, v[6:9] offset:2048
	v_cvt_pk_bf16_f32 v6, v10, v11
	v_cvt_pk_bf16_f32 v7, v12, v13
	v_cvt_pk_bf16_f32 v8, v14, v15
	v_cvt_pk_bf16_f32 v9, v16, v17
	ds_write_b128 v165, v[6:9] offset:3072
	s_and_saveexec_b64 s[16:17], s[4:5]
	v_add_u32_e32 v5, s8, v171
	ds_write_b32 v5, v3 offset:4096
	s_or_b64 exec, exec, s[16:17]
	s_waitcnt lgkmcnt(4)
	v_add_f32_e32 v2, v2, v4
	v_fmac_f32_e32 v2, v0, v3
	v_mov_b32_e32 v0, v2
	s_branch .LBB0_414
